# expert list sort made deterministic (full rank by unique key via LDS broadcast compares) instead of LDS-atomic counting sort
# baseline (speedup 1.0000x reference)
.LBB0_1944:
	s_waitcnt vmcnt(0) lgkmcnt(0)
	v_readfirstlane_b32 s100, v206
	s_lshr_b32 s100, s100, 6
	s_lshl_b32 s100, s100, 12
	s_add_u32 s100, s100, 0x4000
	v_and_b32_e32 v62, 63, v206
	v_lshl_add_u32 v63, v62, 2, s100
	v_mov_b32_e32 v64, s100
	ds_read_b64 v[52:53], v175
	ds_read_b64 v[54:55], v175 offset:1024
	s_waitcnt lgkmcnt(0)
	v_lshl_or_b32 v56, v52, 7, v62
	v_or_b32_e32 v57, 64, v62
	v_lshl_or_b32 v57, v54, 7, v57
	ds_write_b32 v63, v56
	ds_write_b32 v63, v57 offset:256
	v_mov_b32_e32 v58, 0
	v_mov_b32_e32 v59, 0
	ds_read_b128 v[66:69], v64 offset:0
	ds_read_b128 v[70:73], v64 offset:16
	s_waitcnt lgkmcnt(1)
	v_cmp_lt_u32_e64 s[20:21], v66, v56
	v_cmp_lt_u32_e64 s[22:23], v66, v57
	v_cmp_lt_u32_e64 s[24:25], v67, v56
	v_cmp_lt_u32_e64 s[26:27], v67, v57
	v_addc_co_u32_e64 v58, s[18:19], 0, v58, s[20:21]
	v_cmp_lt_u32_e64 s[28:29], v68, v56
	v_addc_co_u32_e64 v59, s[18:19], 0, v59, s[22:23]
	v_cmp_lt_u32_e64 s[30:31], v68, v57
	v_addc_co_u32_e64 v58, s[18:19], 0, v58, s[24:25]
	v_cmp_lt_u32_e64 s[20:21], v69, v56
	v_addc_co_u32_e64 v59, s[18:19], 0, v59, s[26:27]
	v_cmp_lt_u32_e64 s[22:23], v69, v57
	v_addc_co_u32_e64 v58, s[18:19], 0, v58, s[28:29]
	ds_read_b128 v[66:69], v64 offset:32
	s_waitcnt lgkmcnt(1)
	v_cmp_lt_u32_e64 s[24:25], v70, v56
	v_addc_co_u32_e64 v59, s[18:19], 0, v59, s[30:31]
	v_cmp_lt_u32_e64 s[26:27], v70, v57
	v_addc_co_u32_e64 v58, s[18:19], 0, v58, s[20:21]
	v_cmp_lt_u32_e64 s[28:29], v71, v56
	v_addc_co_u32_e64 v59, s[18:19], 0, v59, s[22:23]
	v_cmp_lt_u32_e64 s[30:31], v71, v57
	v_addc_co_u32_e64 v58, s[18:19], 0, v58, s[24:25]
	v_cmp_lt_u32_e64 s[20:21], v72, v56
	v_addc_co_u32_e64 v59, s[18:19], 0, v59, s[26:27]
	v_cmp_lt_u32_e64 s[22:23], v72, v57
	v_addc_co_u32_e64 v58, s[18:19], 0, v58, s[28:29]
	v_cmp_lt_u32_e64 s[24:25], v73, v56
	v_addc_co_u32_e64 v59, s[18:19], 0, v59, s[30:31]
	v_cmp_lt_u32_e64 s[26:27], v73, v57
	v_addc_co_u32_e64 v58, s[18:19], 0, v58, s[20:21]
	ds_read_b128 v[70:73], v64 offset:48
	s_waitcnt lgkmcnt(1)
	v_cmp_lt_u32_e64 s[28:29], v66, v56
	v_addc_co_u32_e64 v59, s[18:19], 0, v59, s[22:23]
	v_cmp_lt_u32_e64 s[30:31], v66, v57
	v_addc_co_u32_e64 v58, s[18:19], 0, v58, s[24:25]
	v_cmp_lt_u32_e64 s[20:21], v67, v56
	v_addc_co_u32_e64 v59, s[18:19], 0, v59, s[26:27]
	v_cmp_lt_u32_e64 s[22:23], v67, v57
	v_addc_co_u32_e64 v58, s[18:19], 0, v58, s[28:29]
	v_cmp_lt_u32_e64 s[24:25], v68, v56
	v_addc_co_u32_e64 v59, s[18:19], 0, v59, s[30:31]
	v_cmp_lt_u32_e64 s[26:27], v68, v57
	v_addc_co_u32_e64 v58, s[18:19], 0, v58, s[20:21]
	v_cmp_lt_u32_e64 s[28:29], v69, v56
	v_addc_co_u32_e64 v59, s[18:19], 0, v59, s[22:23]
	v_cmp_lt_u32_e64 s[30:31], v69, v57
	v_addc_co_u32_e64 v58, s[18:19], 0, v58, s[24:25]
	ds_read_b128 v[66:69], v64 offset:64
	s_waitcnt lgkmcnt(1)
	v_cmp_lt_u32_e64 s[20:21], v70, v56
	v_addc_co_u32_e64 v59, s[18:19], 0, v59, s[26:27]
	v_cmp_lt_u32_e64 s[22:23], v70, v57
	v_addc_co_u32_e64 v58, s[18:19], 0, v58, s[28:29]
	v_cmp_lt_u32_e64 s[24:25], v71, v56
	v_addc_co_u32_e64 v59, s[18:19], 0, v59, s[30:31]
	v_cmp_lt_u32_e64 s[26:27], v71, v57
	v_addc_co_u32_e64 v58, s[18:19], 0, v58, s[20:21]
	v_cmp_lt_u32_e64 s[28:29], v72, v56
	v_addc_co_u32_e64 v59, s[18:19], 0, v59, s[22:23]
	v_cmp_lt_u32_e64 s[30:31], v72, v57
	v_addc_co_u32_e64 v58, s[18:19], 0, v58, s[24:25]
	v_cmp_lt_u32_e64 s[20:21], v73, v56
	v_addc_co_u32_e64 v59, s[18:19], 0, v59, s[26:27]
	v_cmp_lt_u32_e64 s[22:23], v73, v57
	v_addc_co_u32_e64 v58, s[18:19], 0, v58, s[28:29]
	ds_read_b128 v[70:73], v64 offset:80
	s_waitcnt lgkmcnt(1)
	v_cmp_lt_u32_e64 s[24:25], v66, v56
	v_addc_co_u32_e64 v59, s[18:19], 0, v59, s[30:31]
	v_cmp_lt_u32_e64 s[26:27], v66, v57
	v_addc_co_u32_e64 v58, s[18:19], 0, v58, s[20:21]
	v_cmp_lt_u32_e64 s[28:29], v67, v56
	v_addc_co_u32_e64 v59, s[18:19], 0, v59, s[22:23]
	v_cmp_lt_u32_e64 s[30:31], v67, v57
	v_addc_co_u32_e64 v58, s[18:19], 0, v58, s[24:25]
	v_cmp_lt_u32_e64 s[20:21], v68, v56
	v_addc_co_u32_e64 v59, s[18:19], 0, v59, s[26:27]
	v_cmp_lt_u32_e64 s[22:23], v68, v57
	v_addc_co_u32_e64 v58, s[18:19], 0, v58, s[28:29]
	v_cmp_lt_u32_e64 s[24:25], v69, v56
	v_addc_co_u32_e64 v59, s[18:19], 0, v59, s[30:31]
	v_cmp_lt_u32_e64 s[26:27], v69, v57
	v_addc_co_u32_e64 v58, s[18:19], 0, v58, s[20:21]
	ds_read_b128 v[66:69], v64 offset:96
	s_waitcnt lgkmcnt(1)
	v_cmp_lt_u32_e64 s[28:29], v70, v56
	v_addc_co_u32_e64 v59, s[18:19], 0, v59, s[22:23]
	v_cmp_lt_u32_e64 s[30:31], v70, v57
	v_addc_co_u32_e64 v58, s[18:19], 0, v58, s[24:25]
	v_cmp_lt_u32_e64 s[20:21], v71, v56
	v_addc_co_u32_e64 v59, s[18:19], 0, v59, s[26:27]
	v_cmp_lt_u32_e64 s[22:23], v71, v57
	v_addc_co_u32_e64 v58, s[18:19], 0, v58, s[28:29]
	v_cmp_lt_u32_e64 s[24:25], v72, v56
	v_addc_co_u32_e64 v59, s[18:19], 0, v59, s[30:31]
	v_cmp_lt_u32_e64 s[26:27], v72, v57
	v_addc_co_u32_e64 v58, s[18:19], 0, v58, s[20:21]
	v_cmp_lt_u32_e64 s[28:29], v73, v56
	v_addc_co_u32_e64 v59, s[18:19], 0, v59, s[22:23]
	v_cmp_lt_u32_e64 s[30:31], v73, v57
	v_addc_co_u32_e64 v58, s[18:19], 0, v58, s[24:25]
	ds_read_b128 v[70:73], v64 offset:112
	s_waitcnt lgkmcnt(1)
	v_cmp_lt_u32_e64 s[20:21], v66, v56
	v_addc_co_u32_e64 v59, s[18:19], 0, v59, s[26:27]
	v_cmp_lt_u32_e64 s[22:23], v66, v57
	v_addc_co_u32_e64 v58, s[18:19], 0, v58, s[28:29]
	v_cmp_lt_u32_e64 s[24:25], v67, v56
	v_addc_co_u32_e64 v59, s[18:19], 0, v59, s[30:31]
	v_cmp_lt_u32_e64 s[26:27], v67, v57
	v_addc_co_u32_e64 v58, s[18:19], 0, v58, s[20:21]
	v_cmp_lt_u32_e64 s[28:29], v68, v56
	v_addc_co_u32_e64 v59, s[18:19], 0, v59, s[22:23]
	v_cmp_lt_u32_e64 s[30:31], v68, v57
	v_addc_co_u32_e64 v58, s[18:19], 0, v58, s[24:25]
	v_cmp_lt_u32_e64 s[20:21], v69, v56
	v_addc_co_u32_e64 v59, s[18:19], 0, v59, s[26:27]
	v_cmp_lt_u32_e64 s[22:23], v69, v57
	v_addc_co_u32_e64 v58, s[18:19], 0, v58, s[28:29]
	ds_read_b128 v[66:69], v64 offset:128
	s_waitcnt lgkmcnt(1)
	v_cmp_lt_u32_e64 s[24:25], v70, v56
	v_addc_co_u32_e64 v59, s[18:19], 0, v59, s[30:31]
	v_cmp_lt_u32_e64 s[26:27], v70, v57
	v_addc_co_u32_e64 v58, s[18:19], 0, v58, s[20:21]
	v_cmp_lt_u32_e64 s[28:29], v71, v56
	v_addc_co_u32_e64 v59, s[18:19], 0, v59, s[22:23]
	v_cmp_lt_u32_e64 s[30:31], v71, v57
	v_addc_co_u32_e64 v58, s[18:19], 0, v58, s[24:25]
	v_cmp_lt_u32_e64 s[20:21], v72, v56
	v_addc_co_u32_e64 v59, s[18:19], 0, v59, s[26:27]
	v_cmp_lt_u32_e64 s[22:23], v72, v57
	v_addc_co_u32_e64 v58, s[18:19], 0, v58, s[28:29]
	v_cmp_lt_u32_e64 s[24:25], v73, v56
	v_addc_co_u32_e64 v59, s[18:19], 0, v59, s[30:31]
	v_cmp_lt_u32_e64 s[26:27], v73, v57
	v_addc_co_u32_e64 v58, s[18:19], 0, v58, s[20:21]
	ds_read_b128 v[70:73], v64 offset:144
	s_waitcnt lgkmcnt(1)
	v_cmp_lt_u32_e64 s[28:29], v66, v56
	v_addc_co_u32_e64 v59, s[18:19], 0, v59, s[22:23]
	v_cmp_lt_u32_e64 s[30:31], v66, v57
	v_addc_co_u32_e64 v58, s[18:19], 0, v58, s[24:25]
	v_cmp_lt_u32_e64 s[20:21], v67, v56
	v_addc_co_u32_e64 v59, s[18:19], 0, v59, s[26:27]
	v_cmp_lt_u32_e64 s[22:23], v67, v57
	v_addc_co_u32_e64 v58, s[18:19], 0, v58, s[28:29]
	v_cmp_lt_u32_e64 s[24:25], v68, v56
	v_addc_co_u32_e64 v59, s[18:19], 0, v59, s[30:31]
	v_cmp_lt_u32_e64 s[26:27], v68, v57
	v_addc_co_u32_e64 v58, s[18:19], 0, v58, s[20:21]
	v_cmp_lt_u32_e64 s[28:29], v69, v56
	v_addc_co_u32_e64 v59, s[18:19], 0, v59, s[22:23]
	v_cmp_lt_u32_e64 s[30:31], v69, v57
	v_addc_co_u32_e64 v58, s[18:19], 0, v58, s[24:25]
	ds_read_b128 v[66:69], v64 offset:160
	s_waitcnt lgkmcnt(1)
	v_cmp_lt_u32_e64 s[20:21], v70, v56
	v_addc_co_u32_e64 v59, s[18:19], 0, v59, s[26:27]
	v_cmp_lt_u32_e64 s[22:23], v70, v57
	v_addc_co_u32_e64 v58, s[18:19], 0, v58, s[28:29]
	v_cmp_lt_u32_e64 s[24:25], v71, v56
	v_addc_co_u32_e64 v59, s[18:19], 0, v59, s[30:31]
	v_cmp_lt_u32_e64 s[26:27], v71, v57
	v_addc_co_u32_e64 v58, s[18:19], 0, v58, s[20:21]
	v_cmp_lt_u32_e64 s[28:29], v72, v56
	v_addc_co_u32_e64 v59, s[18:19], 0, v59, s[22:23]
	v_cmp_lt_u32_e64 s[30:31], v72, v57
	v_addc_co_u32_e64 v58, s[18:19], 0, v58, s[24:25]
	v_cmp_lt_u32_e64 s[20:21], v73, v56
	v_addc_co_u32_e64 v59, s[18:19], 0, v59, s[26:27]
	v_cmp_lt_u32_e64 s[22:23], v73, v57
	v_addc_co_u32_e64 v58, s[18:19], 0, v58, s[28:29]
	ds_read_b128 v[70:73], v64 offset:176
	s_waitcnt lgkmcnt(1)
	v_cmp_lt_u32_e64 s[24:25], v66, v56
	v_addc_co_u32_e64 v59, s[18:19], 0, v59, s[30:31]
	v_cmp_lt_u32_e64 s[26:27], v66, v57
	v_addc_co_u32_e64 v58, s[18:19], 0, v58, s[20:21]
	v_cmp_lt_u32_e64 s[28:29], v67, v56
	v_addc_co_u32_e64 v59, s[18:19], 0, v59, s[22:23]
	v_cmp_lt_u32_e64 s[30:31], v67, v57
	v_addc_co_u32_e64 v58, s[18:19], 0, v58, s[24:25]
	v_cmp_lt_u32_e64 s[20:21], v68, v56
	v_addc_co_u32_e64 v59, s[18:19], 0, v59, s[26:27]
	v_cmp_lt_u32_e64 s[22:23], v68, v57
	v_addc_co_u32_e64 v58, s[18:19], 0, v58, s[28:29]
	v_cmp_lt_u32_e64 s[24:25], v69, v56
	v_addc_co_u32_e64 v59, s[18:19], 0, v59, s[30:31]
	v_cmp_lt_u32_e64 s[26:27], v69, v57
	v_addc_co_u32_e64 v58, s[18:19], 0, v58, s[20:21]
	ds_read_b128 v[66:69], v64 offset:192
	s_waitcnt lgkmcnt(1)
	v_cmp_lt_u32_e64 s[28:29], v70, v56
	v_addc_co_u32_e64 v59, s[18:19], 0, v59, s[22:23]
	v_cmp_lt_u32_e64 s[30:31], v70, v57
	v_addc_co_u32_e64 v58, s[18:19], 0, v58, s[24:25]
	v_cmp_lt_u32_e64 s[20:21], v71, v56
	v_addc_co_u32_e64 v59, s[18:19], 0, v59, s[26:27]
	v_cmp_lt_u32_e64 s[22:23], v71, v57
	v_addc_co_u32_e64 v58, s[18:19], 0, v58, s[28:29]
	v_cmp_lt_u32_e64 s[24:25], v72, v56
	v_addc_co_u32_e64 v59, s[18:19], 0, v59, s[30:31]
	v_cmp_lt_u32_e64 s[26:27], v72, v57
	v_addc_co_u32_e64 v58, s[18:19], 0, v58, s[20:21]
	v_cmp_lt_u32_e64 s[28:29], v73, v56
	v_addc_co_u32_e64 v59, s[18:19], 0, v59, s[22:23]
	v_cmp_lt_u32_e64 s[30:31], v73, v57
	v_addc_co_u32_e64 v58, s[18:19], 0, v58, s[24:25]
	ds_read_b128 v[70:73], v64 offset:208
	s_waitcnt lgkmcnt(1)
	v_cmp_lt_u32_e64 s[20:21], v66, v56
	v_addc_co_u32_e64 v59, s[18:19], 0, v59, s[26:27]
	v_cmp_lt_u32_e64 s[22:23], v66, v57
	v_addc_co_u32_e64 v58, s[18:19], 0, v58, s[28:29]
	v_cmp_lt_u32_e64 s[24:25], v67, v56
	v_addc_co_u32_e64 v59, s[18:19], 0, v59, s[30:31]
	v_cmp_lt_u32_e64 s[26:27], v67, v57
	v_addc_co_u32_e64 v58, s[18:19], 0, v58, s[20:21]
	v_cmp_lt_u32_e64 s[28:29], v68, v56
	v_addc_co_u32_e64 v59, s[18:19], 0, v59, s[22:23]
	v_cmp_lt_u32_e64 s[30:31], v68, v57
	v_addc_co_u32_e64 v58, s[18:19], 0, v58, s[24:25]
	v_cmp_lt_u32_e64 s[20:21], v69, v56
	v_addc_co_u32_e64 v59, s[18:19], 0, v59, s[26:27]
	v_cmp_lt_u32_e64 s[22:23], v69, v57
	v_addc_co_u32_e64 v58, s[18:19], 0, v58, s[28:29]
	ds_read_b128 v[66:69], v64 offset:224
	s_waitcnt lgkmcnt(1)
	v_cmp_lt_u32_e64 s[24:25], v70, v56
	v_addc_co_u32_e64 v59, s[18:19], 0, v59, s[30:31]
	v_cmp_lt_u32_e64 s[26:27], v70, v57
	v_addc_co_u32_e64 v58, s[18:19], 0, v58, s[20:21]
	v_cmp_lt_u32_e64 s[28:29], v71, v56
	v_addc_co_u32_e64 v59, s[18:19], 0, v59, s[22:23]
	v_cmp_lt_u32_e64 s[30:31], v71, v57
	v_addc_co_u32_e64 v58, s[18:19], 0, v58, s[24:25]
	v_cmp_lt_u32_e64 s[20:21], v72, v56
	v_addc_co_u32_e64 v59, s[18:19], 0, v59, s[26:27]
	v_cmp_lt_u32_e64 s[22:23], v72, v57
	v_addc_co_u32_e64 v58, s[18:19], 0, v58, s[28:29]
	v_cmp_lt_u32_e64 s[24:25], v73, v56
	v_addc_co_u32_e64 v59, s[18:19], 0, v59, s[30:31]
	v_cmp_lt_u32_e64 s[26:27], v73, v57
	v_addc_co_u32_e64 v58, s[18:19], 0, v58, s[20:21]
	ds_read_b128 v[70:73], v64 offset:240
	s_waitcnt lgkmcnt(1)
	v_cmp_lt_u32_e64 s[28:29], v66, v56
	v_addc_co_u32_e64 v59, s[18:19], 0, v59, s[22:23]
	v_cmp_lt_u32_e64 s[30:31], v66, v57
	v_addc_co_u32_e64 v58, s[18:19], 0, v58, s[24:25]
	v_cmp_lt_u32_e64 s[20:21], v67, v56
	v_addc_co_u32_e64 v59, s[18:19], 0, v59, s[26:27]
	v_cmp_lt_u32_e64 s[22:23], v67, v57
	v_addc_co_u32_e64 v58, s[18:19], 0, v58, s[28:29]
	v_cmp_lt_u32_e64 s[24:25], v68, v56
	v_addc_co_u32_e64 v59, s[18:19], 0, v59, s[30:31]
	v_cmp_lt_u32_e64 s[26:27], v68, v57
	v_addc_co_u32_e64 v58, s[18:19], 0, v58, s[20:21]
	v_cmp_lt_u32_e64 s[28:29], v69, v56
	v_addc_co_u32_e64 v59, s[18:19], 0, v59, s[22:23]
	v_cmp_lt_u32_e64 s[30:31], v69, v57
	v_addc_co_u32_e64 v58, s[18:19], 0, v58, s[24:25]
	ds_read_b128 v[66:69], v64 offset:256
	s_waitcnt lgkmcnt(1)
	v_cmp_lt_u32_e64 s[20:21], v70, v56
	v_addc_co_u32_e64 v59, s[18:19], 0, v59, s[26:27]
	v_cmp_lt_u32_e64 s[22:23], v70, v57
	v_addc_co_u32_e64 v58, s[18:19], 0, v58, s[28:29]
	v_cmp_lt_u32_e64 s[24:25], v71, v56
	v_addc_co_u32_e64 v59, s[18:19], 0, v59, s[30:31]
	v_cmp_lt_u32_e64 s[26:27], v71, v57
	v_addc_co_u32_e64 v58, s[18:19], 0, v58, s[20:21]
	v_cmp_lt_u32_e64 s[28:29], v72, v56
	v_addc_co_u32_e64 v59, s[18:19], 0, v59, s[22:23]
	v_cmp_lt_u32_e64 s[30:31], v72, v57
	v_addc_co_u32_e64 v58, s[18:19], 0, v58, s[24:25]
	v_cmp_lt_u32_e64 s[20:21], v73, v56
	v_addc_co_u32_e64 v59, s[18:19], 0, v59, s[26:27]
	v_cmp_lt_u32_e64 s[22:23], v73, v57
	v_addc_co_u32_e64 v58, s[18:19], 0, v58, s[28:29]
	ds_read_b128 v[70:73], v64 offset:272
	s_waitcnt lgkmcnt(1)
	v_cmp_lt_u32_e64 s[24:25], v66, v56
	v_addc_co_u32_e64 v59, s[18:19], 0, v59, s[30:31]
	v_cmp_lt_u32_e64 s[26:27], v66, v57
	v_addc_co_u32_e64 v58, s[18:19], 0, v58, s[20:21]
	v_cmp_lt_u32_e64 s[28:29], v67, v56
	v_addc_co_u32_e64 v59, s[18:19], 0, v59, s[22:23]
	v_cmp_lt_u32_e64 s[30:31], v67, v57
	v_addc_co_u32_e64 v58, s[18:19], 0, v58, s[24:25]
	v_cmp_lt_u32_e64 s[20:21], v68, v56
	v_addc_co_u32_e64 v59, s[18:19], 0, v59, s[26:27]
	v_cmp_lt_u32_e64 s[22:23], v68, v57
	v_addc_co_u32_e64 v58, s[18:19], 0, v58, s[28:29]
	v_cmp_lt_u32_e64 s[24:25], v69, v56
	v_addc_co_u32_e64 v59, s[18:19], 0, v59, s[30:31]
	v_cmp_lt_u32_e64 s[26:27], v69, v57
	v_addc_co_u32_e64 v58, s[18:19], 0, v58, s[20:21]
	ds_read_b128 v[66:69], v64 offset:288
	s_waitcnt lgkmcnt(1)
	v_cmp_lt_u32_e64 s[28:29], v70, v56
	v_addc_co_u32_e64 v59, s[18:19], 0, v59, s[22:23]
	v_cmp_lt_u32_e64 s[30:31], v70, v57
	v_addc_co_u32_e64 v58, s[18:19], 0, v58, s[24:25]
	v_cmp_lt_u32_e64 s[20:21], v71, v56
	v_addc_co_u32_e64 v59, s[18:19], 0, v59, s[26:27]
	v_cmp_lt_u32_e64 s[22:23], v71, v57
	v_addc_co_u32_e64 v58, s[18:19], 0, v58, s[28:29]
	v_cmp_lt_u32_e64 s[24:25], v72, v56
	v_addc_co_u32_e64 v59, s[18:19], 0, v59, s[30:31]
	v_cmp_lt_u32_e64 s[26:27], v72, v57
	v_addc_co_u32_e64 v58, s[18:19], 0, v58, s[20:21]
	v_cmp_lt_u32_e64 s[28:29], v73, v56
	v_addc_co_u32_e64 v59, s[18:19], 0, v59, s[22:23]
	v_cmp_lt_u32_e64 s[30:31], v73, v57
	v_addc_co_u32_e64 v58, s[18:19], 0, v58, s[24:25]
	ds_read_b128 v[70:73], v64 offset:304
	s_waitcnt lgkmcnt(1)
	v_cmp_lt_u32_e64 s[20:21], v66, v56
	v_addc_co_u32_e64 v59, s[18:19], 0, v59, s[26:27]
	v_cmp_lt_u32_e64 s[22:23], v66, v57
	v_addc_co_u32_e64 v58, s[18:19], 0, v58, s[28:29]
	v_cmp_lt_u32_e64 s[24:25], v67, v56
	v_addc_co_u32_e64 v59, s[18:19], 0, v59, s[30:31]
	v_cmp_lt_u32_e64 s[26:27], v67, v57
	v_addc_co_u32_e64 v58, s[18:19], 0, v58, s[20:21]
	v_cmp_lt_u32_e64 s[28:29], v68, v56
	v_addc_co_u32_e64 v59, s[18:19], 0, v59, s[22:23]
	v_cmp_lt_u32_e64 s[30:31], v68, v57
	v_addc_co_u32_e64 v58, s[18:19], 0, v58, s[24:25]
	v_cmp_lt_u32_e64 s[20:21], v69, v56
	v_addc_co_u32_e64 v59, s[18:19], 0, v59, s[26:27]
	v_cmp_lt_u32_e64 s[22:23], v69, v57
	v_addc_co_u32_e64 v58, s[18:19], 0, v58, s[28:29]
	ds_read_b128 v[66:69], v64 offset:320
	s_waitcnt lgkmcnt(1)
	v_cmp_lt_u32_e64 s[24:25], v70, v56
	v_addc_co_u32_e64 v59, s[18:19], 0, v59, s[30:31]
	v_cmp_lt_u32_e64 s[26:27], v70, v57
	v_addc_co_u32_e64 v58, s[18:19], 0, v58, s[20:21]
	v_cmp_lt_u32_e64 s[28:29], v71, v56
	v_addc_co_u32_e64 v59, s[18:19], 0, v59, s[22:23]
	v_cmp_lt_u32_e64 s[30:31], v71, v57
	v_addc_co_u32_e64 v58, s[18:19], 0, v58, s[24:25]
	v_cmp_lt_u32_e64 s[20:21], v72, v56
	v_addc_co_u32_e64 v59, s[18:19], 0, v59, s[26:27]
	v_cmp_lt_u32_e64 s[22:23], v72, v57
	v_addc_co_u32_e64 v58, s[18:19], 0, v58, s[28:29]
	v_cmp_lt_u32_e64 s[24:25], v73, v56
	v_addc_co_u32_e64 v59, s[18:19], 0, v59, s[30:31]
	v_cmp_lt_u32_e64 s[26:27], v73, v57
	v_addc_co_u32_e64 v58, s[18:19], 0, v58, s[20:21]
	ds_read_b128 v[70:73], v64 offset:336
	s_waitcnt lgkmcnt(1)
	v_cmp_lt_u32_e64 s[28:29], v66, v56
	v_addc_co_u32_e64 v59, s[18:19], 0, v59, s[22:23]
	v_cmp_lt_u32_e64 s[30:31], v66, v57
	v_addc_co_u32_e64 v58, s[18:19], 0, v58, s[24:25]
	v_cmp_lt_u32_e64 s[20:21], v67, v56
	v_addc_co_u32_e64 v59, s[18:19], 0, v59, s[26:27]
	v_cmp_lt_u32_e64 s[22:23], v67, v57
	v_addc_co_u32_e64 v58, s[18:19], 0, v58, s[28:29]
	v_cmp_lt_u32_e64 s[24:25], v68, v56
	v_addc_co_u32_e64 v59, s[18:19], 0, v59, s[30:31]
	v_cmp_lt_u32_e64 s[26:27], v68, v57
	v_addc_co_u32_e64 v58, s[18:19], 0, v58, s[20:21]
	v_cmp_lt_u32_e64 s[28:29], v69, v56
	v_addc_co_u32_e64 v59, s[18:19], 0, v59, s[22:23]
	v_cmp_lt_u32_e64 s[30:31], v69, v57
	v_addc_co_u32_e64 v58, s[18:19], 0, v58, s[24:25]
	ds_read_b128 v[66:69], v64 offset:352
	s_waitcnt lgkmcnt(1)
	v_cmp_lt_u32_e64 s[20:21], v70, v56
	v_addc_co_u32_e64 v59, s[18:19], 0, v59, s[26:27]
	v_cmp_lt_u32_e64 s[22:23], v70, v57
	v_addc_co_u32_e64 v58, s[18:19], 0, v58, s[28:29]
	v_cmp_lt_u32_e64 s[24:25], v71, v56
	v_addc_co_u32_e64 v59, s[18:19], 0, v59, s[30:31]
	v_cmp_lt_u32_e64 s[26:27], v71, v57
	v_addc_co_u32_e64 v58, s[18:19], 0, v58, s[20:21]
	v_cmp_lt_u32_e64 s[28:29], v72, v56
	v_addc_co_u32_e64 v59, s[18:19], 0, v59, s[22:23]
	v_cmp_lt_u32_e64 s[30:31], v72, v57
	v_addc_co_u32_e64 v58, s[18:19], 0, v58, s[24:25]
	v_cmp_lt_u32_e64 s[20:21], v73, v56
	v_addc_co_u32_e64 v59, s[18:19], 0, v59, s[26:27]
	v_cmp_lt_u32_e64 s[22:23], v73, v57
	v_addc_co_u32_e64 v58, s[18:19], 0, v58, s[28:29]
	ds_read_b128 v[70:73], v64 offset:368
	s_waitcnt lgkmcnt(1)
	v_cmp_lt_u32_e64 s[24:25], v66, v56
	v_addc_co_u32_e64 v59, s[18:19], 0, v59, s[30:31]
	v_cmp_lt_u32_e64 s[26:27], v66, v57
	v_addc_co_u32_e64 v58, s[18:19], 0, v58, s[20:21]
	v_cmp_lt_u32_e64 s[28:29], v67, v56
	v_addc_co_u32_e64 v59, s[18:19], 0, v59, s[22:23]
	v_cmp_lt_u32_e64 s[30:31], v67, v57
	v_addc_co_u32_e64 v58, s[18:19], 0, v58, s[24:25]
	v_cmp_lt_u32_e64 s[20:21], v68, v56
	v_addc_co_u32_e64 v59, s[18:19], 0, v59, s[26:27]
	v_cmp_lt_u32_e64 s[22:23], v68, v57
	v_addc_co_u32_e64 v58, s[18:19], 0, v58, s[28:29]
	v_cmp_lt_u32_e64 s[24:25], v69, v56
	v_addc_co_u32_e64 v59, s[18:19], 0, v59, s[30:31]
	v_cmp_lt_u32_e64 s[26:27], v69, v57
	v_addc_co_u32_e64 v58, s[18:19], 0, v58, s[20:21]
	ds_read_b128 v[66:69], v64 offset:384
	s_waitcnt lgkmcnt(1)
	v_cmp_lt_u32_e64 s[28:29], v70, v56
	v_addc_co_u32_e64 v59, s[18:19], 0, v59, s[22:23]
	v_cmp_lt_u32_e64 s[30:31], v70, v57
	v_addc_co_u32_e64 v58, s[18:19], 0, v58, s[24:25]
	v_cmp_lt_u32_e64 s[20:21], v71, v56
	v_addc_co_u32_e64 v59, s[18:19], 0, v59, s[26:27]
	v_cmp_lt_u32_e64 s[22:23], v71, v57
	v_addc_co_u32_e64 v58, s[18:19], 0, v58, s[28:29]
	v_cmp_lt_u32_e64 s[24:25], v72, v56
	v_addc_co_u32_e64 v59, s[18:19], 0, v59, s[30:31]
	v_cmp_lt_u32_e64 s[26:27], v72, v57
	v_addc_co_u32_e64 v58, s[18:19], 0, v58, s[20:21]
	v_cmp_lt_u32_e64 s[28:29], v73, v56
	v_addc_co_u32_e64 v59, s[18:19], 0, v59, s[22:23]
	v_cmp_lt_u32_e64 s[30:31], v73, v57
	v_addc_co_u32_e64 v58, s[18:19], 0, v58, s[24:25]
	ds_read_b128 v[70:73], v64 offset:400
	s_waitcnt lgkmcnt(1)
	v_cmp_lt_u32_e64 s[20:21], v66, v56
	v_addc_co_u32_e64 v59, s[18:19], 0, v59, s[26:27]
	v_cmp_lt_u32_e64 s[22:23], v66, v57
	v_addc_co_u32_e64 v58, s[18:19], 0, v58, s[28:29]
	v_cmp_lt_u32_e64 s[24:25], v67, v56
	v_addc_co_u32_e64 v59, s[18:19], 0, v59, s[30:31]
	v_cmp_lt_u32_e64 s[26:27], v67, v57
	v_addc_co_u32_e64 v58, s[18:19], 0, v58, s[20:21]
	v_cmp_lt_u32_e64 s[28:29], v68, v56
	v_addc_co_u32_e64 v59, s[18:19], 0, v59, s[22:23]
	v_cmp_lt_u32_e64 s[30:31], v68, v57
	v_addc_co_u32_e64 v58, s[18:19], 0, v58, s[24:25]
	v_cmp_lt_u32_e64 s[20:21], v69, v56
	v_addc_co_u32_e64 v59, s[18:19], 0, v59, s[26:27]
	v_cmp_lt_u32_e64 s[22:23], v69, v57
	v_addc_co_u32_e64 v58, s[18:19], 0, v58, s[28:29]
	ds_read_b128 v[66:69], v64 offset:416
	s_waitcnt lgkmcnt(1)
	v_cmp_lt_u32_e64 s[24:25], v70, v56
	v_addc_co_u32_e64 v59, s[18:19], 0, v59, s[30:31]
	v_cmp_lt_u32_e64 s[26:27], v70, v57
	v_addc_co_u32_e64 v58, s[18:19], 0, v58, s[20:21]
	v_cmp_lt_u32_e64 s[28:29], v71, v56
	v_addc_co_u32_e64 v59, s[18:19], 0, v59, s[22:23]
	v_cmp_lt_u32_e64 s[30:31], v71, v57
	v_addc_co_u32_e64 v58, s[18:19], 0, v58, s[24:25]
	v_cmp_lt_u32_e64 s[20:21], v72, v56
	v_addc_co_u32_e64 v59, s[18:19], 0, v59, s[26:27]
	v_cmp_lt_u32_e64 s[22:23], v72, v57
	v_addc_co_u32_e64 v58, s[18:19], 0, v58, s[28:29]
	v_cmp_lt_u32_e64 s[24:25], v73, v56
	v_addc_co_u32_e64 v59, s[18:19], 0, v59, s[30:31]
	v_cmp_lt_u32_e64 s[26:27], v73, v57
	v_addc_co_u32_e64 v58, s[18:19], 0, v58, s[20:21]
	ds_read_b128 v[70:73], v64 offset:432
	s_waitcnt lgkmcnt(1)
	v_cmp_lt_u32_e64 s[28:29], v66, v56
	v_addc_co_u32_e64 v59, s[18:19], 0, v59, s[22:23]
	v_cmp_lt_u32_e64 s[30:31], v66, v57
	v_addc_co_u32_e64 v58, s[18:19], 0, v58, s[24:25]
	v_cmp_lt_u32_e64 s[20:21], v67, v56
	v_addc_co_u32_e64 v59, s[18:19], 0, v59, s[26:27]
	v_cmp_lt_u32_e64 s[22:23], v67, v57
	v_addc_co_u32_e64 v58, s[18:19], 0, v58, s[28:29]
	v_cmp_lt_u32_e64 s[24:25], v68, v56
	v_addc_co_u32_e64 v59, s[18:19], 0, v59, s[30:31]
	v_cmp_lt_u32_e64 s[26:27], v68, v57
	v_addc_co_u32_e64 v58, s[18:19], 0, v58, s[20:21]
	v_cmp_lt_u32_e64 s[28:29], v69, v56
	v_addc_co_u32_e64 v59, s[18:19], 0, v59, s[22:23]
	v_cmp_lt_u32_e64 s[30:31], v69, v57
	v_addc_co_u32_e64 v58, s[18:19], 0, v58, s[24:25]
	ds_read_b128 v[66:69], v64 offset:448
	s_waitcnt lgkmcnt(1)
	v_cmp_lt_u32_e64 s[20:21], v70, v56
	v_addc_co_u32_e64 v59, s[18:19], 0, v59, s[26:27]
	v_cmp_lt_u32_e64 s[22:23], v70, v57
	v_addc_co_u32_e64 v58, s[18:19], 0, v58, s[28:29]
	v_cmp_lt_u32_e64 s[24:25], v71, v56
	v_addc_co_u32_e64 v59, s[18:19], 0, v59, s[30:31]
	v_cmp_lt_u32_e64 s[26:27], v71, v57
	v_addc_co_u32_e64 v58, s[18:19], 0, v58, s[20:21]
	v_cmp_lt_u32_e64 s[28:29], v72, v56
	v_addc_co_u32_e64 v59, s[18:19], 0, v59, s[22:23]
	v_cmp_lt_u32_e64 s[30:31], v72, v57
	v_addc_co_u32_e64 v58, s[18:19], 0, v58, s[24:25]
	v_cmp_lt_u32_e64 s[20:21], v73, v56
	v_addc_co_u32_e64 v59, s[18:19], 0, v59, s[26:27]
	v_cmp_lt_u32_e64 s[22:23], v73, v57
	v_addc_co_u32_e64 v58, s[18:19], 0, v58, s[28:29]
	ds_read_b128 v[70:73], v64 offset:464
	s_waitcnt lgkmcnt(1)
	v_cmp_lt_u32_e64 s[24:25], v66, v56
	v_addc_co_u32_e64 v59, s[18:19], 0, v59, s[30:31]
	v_cmp_lt_u32_e64 s[26:27], v66, v57
	v_addc_co_u32_e64 v58, s[18:19], 0, v58, s[20:21]
	v_cmp_lt_u32_e64 s[28:29], v67, v56
	v_addc_co_u32_e64 v59, s[18:19], 0, v59, s[22:23]
	v_cmp_lt_u32_e64 s[30:31], v67, v57
	v_addc_co_u32_e64 v58, s[18:19], 0, v58, s[24:25]
	v_cmp_lt_u32_e64 s[20:21], v68, v56
	v_addc_co_u32_e64 v59, s[18:19], 0, v59, s[26:27]
	v_cmp_lt_u32_e64 s[22:23], v68, v57
	v_addc_co_u32_e64 v58, s[18:19], 0, v58, s[28:29]
	v_cmp_lt_u32_e64 s[24:25], v69, v56
	v_addc_co_u32_e64 v59, s[18:19], 0, v59, s[30:31]
	v_cmp_lt_u32_e64 s[26:27], v69, v57
	v_addc_co_u32_e64 v58, s[18:19], 0, v58, s[20:21]
	ds_read_b128 v[66:69], v64 offset:480
	s_waitcnt lgkmcnt(1)
	v_cmp_lt_u32_e64 s[28:29], v70, v56
	v_addc_co_u32_e64 v59, s[18:19], 0, v59, s[22:23]
	v_cmp_lt_u32_e64 s[30:31], v70, v57
	v_addc_co_u32_e64 v58, s[18:19], 0, v58, s[24:25]
	v_cmp_lt_u32_e64 s[20:21], v71, v56
	v_addc_co_u32_e64 v59, s[18:19], 0, v59, s[26:27]
	v_cmp_lt_u32_e64 s[22:23], v71, v57
	v_addc_co_u32_e64 v58, s[18:19], 0, v58, s[28:29]
	v_cmp_lt_u32_e64 s[24:25], v72, v56
	v_addc_co_u32_e64 v59, s[18:19], 0, v59, s[30:31]
	v_cmp_lt_u32_e64 s[26:27], v72, v57
	v_addc_co_u32_e64 v58, s[18:19], 0, v58, s[20:21]
	v_cmp_lt_u32_e64 s[28:29], v73, v56
	v_addc_co_u32_e64 v59, s[18:19], 0, v59, s[22:23]
	v_cmp_lt_u32_e64 s[30:31], v73, v57
	v_addc_co_u32_e64 v58, s[18:19], 0, v58, s[24:25]
	ds_read_b128 v[70:73], v64 offset:496
	s_waitcnt lgkmcnt(1)
	v_cmp_lt_u32_e64 s[20:21], v66, v56
	v_addc_co_u32_e64 v59, s[18:19], 0, v59, s[26:27]
	v_cmp_lt_u32_e64 s[22:23], v66, v57
	v_addc_co_u32_e64 v58, s[18:19], 0, v58, s[28:29]
	v_cmp_lt_u32_e64 s[24:25], v67, v56
	v_addc_co_u32_e64 v59, s[18:19], 0, v59, s[30:31]
	v_cmp_lt_u32_e64 s[26:27], v67, v57
	v_addc_co_u32_e64 v58, s[18:19], 0, v58, s[20:21]
	v_cmp_lt_u32_e64 s[28:29], v68, v56
	v_addc_co_u32_e64 v59, s[18:19], 0, v59, s[22:23]
	v_cmp_lt_u32_e64 s[30:31], v68, v57
	v_addc_co_u32_e64 v58, s[18:19], 0, v58, s[24:25]
	v_cmp_lt_u32_e64 s[20:21], v69, v56
	v_addc_co_u32_e64 v59, s[18:19], 0, v59, s[26:27]
	v_cmp_lt_u32_e64 s[22:23], v69, v57
	v_addc_co_u32_e64 v58, s[18:19], 0, v58, s[28:29]
	s_waitcnt lgkmcnt(0)
	v_cmp_lt_u32_e64 s[24:25], v70, v56
	v_addc_co_u32_e64 v59, s[18:19], 0, v59, s[30:31]
	v_cmp_lt_u32_e64 s[26:27], v70, v57
	v_addc_co_u32_e64 v58, s[18:19], 0, v58, s[20:21]
	v_cmp_lt_u32_e64 s[28:29], v71, v56
	v_addc_co_u32_e64 v59, s[18:19], 0, v59, s[22:23]
	v_cmp_lt_u32_e64 s[30:31], v71, v57
	v_addc_co_u32_e64 v58, s[18:19], 0, v58, s[24:25]
	v_cmp_lt_u32_e64 s[20:21], v72, v56
	v_addc_co_u32_e64 v59, s[18:19], 0, v59, s[26:27]
	v_cmp_lt_u32_e64 s[22:23], v72, v57
	v_addc_co_u32_e64 v58, s[18:19], 0, v58, s[28:29]
	v_cmp_lt_u32_e64 s[24:25], v73, v56
	v_addc_co_u32_e64 v59, s[18:19], 0, v59, s[30:31]
	v_cmp_lt_u32_e64 s[26:27], v73, v57
	v_addc_co_u32_e64 v58, s[18:19], 0, v58, s[20:21]
	s_nop 1
	v_addc_co_u32_e64 v59, s[18:19], 0, v59, s[22:23]
	v_addc_co_u32_e64 v58, s[18:19], 0, v58, s[24:25]
	v_addc_co_u32_e64 v59, s[18:19], 0, v59, s[26:27]
	v_lshl_add_u32 v58, v58, 4, v174
	v_lshl_add_u32 v59, v59, 4, v174
	ds_write_b64 v58, v[52:53]
	ds_write_b64 v59, v[54:55]
	v_pk_add_f32 v[34:35], v[34:35], 1.0 op_sel_hi:[1,0]
	v_pk_add_f32 v[20:21], v[20:21], 1.0 op_sel_hi:[1,0]
	v_pk_fma_f32 v[132:133], v[0:1], v[34:35], v[38:39]
	v_pk_add_f32 v[34:35], v[36:37], 1.0 op_sel_hi:[1,0]
	v_pk_fma_f32 v[136:137], v[4:5], v[20:21], v[24:25]
	v_pk_add_f32 v[20:21], v[22:23], 1.0 op_sel_hi:[1,0]
	v_pk_fma_f32 v[134:135], v[2:3], v[34:35], v[40:41]
	v_pk_fma_f32 v[138:139], v[6:7], v[20:21], v[26:27]
	v_pk_add_f32 v[20:21], v[28:29], 1.0 op_sel_hi:[1,0]
	s_nop 0
	v_pk_fma_f32 v[140:141], v[8:9], v[20:21], v[42:43]
	v_pk_add_f32 v[20:21], v[30:31], 1.0 op_sel_hi:[1,0]
	s_nop 0
	v_pk_fma_f32 v[30:31], v[10:11], v[20:21], v[44:45]
	v_add_f32_e32 v20, 1.0, v46
	v_add_f32_e32 v21, 1.0, v47
	v_fma_f32 v16, v12, v20, v16
	v_add_f32_e32 v20, 1.0, v48
	v_fmac_f32_e32 v17, v13, v21
	v_add_f32_e32 v21, 1.0, v49
	v_pk_fma_f32 v[142:143], v[14:15], v[20:21], v[18:19]
	ds_read_b32 v166, v175
	ds_read_b32 v167, v175 offset:1024
	v_readlane_b32 s0, v251, 40
	v_readlane_b32 s1, v251, 41
	v_readlane_b32 s6, v251, 42
	v_readlane_b32 s7, v251, 43
	v_readfirstlane_b32 s16, v104
	v_readfirstlane_b32 s17, v105
	v_and_b32_e32 v103, 63, v206
	v_lshlrev_b32_e32 v103, 4, v103
	v_and_b32_e32 v169, 3, v206
	v_lshl_add_u32 v169, v169, 4, v174
	s_mov_b32 s2, 0xaaaaaaaa
	s_mov_b32 s3, 0xaaaaaaaa
	s_mov_b32 s4, 0xcccccccc
	s_mov_b32 s5, 0xcccccccc
	s_waitcnt lgkmcnt(0)
	v_lshlrev_b32_e32 v166, 2, v166
	v_lshlrev_b32_e32 v167, 2, v167
	global_load_dword v26, v166, s[0:1]
	global_load_dword v27, v166, s[6:7]
	global_load_dword v28, v167, s[0:1]
	global_load_dword v29, v167, s[6:7]
	ds_read_b32 v148, v169 offset:0
	s_waitcnt lgkmcnt(0)
	v_mov_b32_dpp v182, v148 quad_perm:[0,0,0,0] row_mask:0xf bank_mask:0xf
	v_mov_b32_dpp v183, v148 quad_perm:[1,1,1,1] row_mask:0xf bank_mask:0xf
	v_mov_b32_dpp v184, v148 quad_perm:[2,2,2,2] row_mask:0xf bank_mask:0xf
	v_mov_b32_dpp v125, v148 quad_perm:[3,3,3,3] row_mask:0xf bank_mask:0xf
	v_lshl_add_u32 v182, v182, 11, v103
	v_lshl_add_u32 v183, v183, 11, v103
	v_lshl_add_u32 v184, v184, 11, v103
	v_lshl_add_u32 v125, v125, 11, v103
	global_load_dwordx4 v[34:37], v182, s[16:17]
	global_load_dwordx4 v[42:45], v183, s[16:17]
	global_load_dwordx4 v[50:53], v184, s[16:17]
	global_load_dwordx4 v[58:61], v125, s[16:17]
	global_load_dwordx4 v[38:41], v182, s[16:17] offset:1024
	global_load_dwordx4 v[46:49], v183, s[16:17] offset:1024
	global_load_dwordx4 v[54:57], v184, s[16:17] offset:1024
	global_load_dwordx4 v[62:65], v125, s[16:17] offset:1024
	ds_read_b32 v148, v169 offset:64
	s_waitcnt lgkmcnt(0)
	v_mov_b32_dpp v182, v148 quad_perm:[0,0,0,0] row_mask:0xf bank_mask:0xf
	v_mov_b32_dpp v183, v148 quad_perm:[1,1,1,1] row_mask:0xf bank_mask:0xf
	v_mov_b32_dpp v184, v148 quad_perm:[2,2,2,2] row_mask:0xf bank_mask:0xf
	v_mov_b32_dpp v125, v148 quad_perm:[3,3,3,3] row_mask:0xf bank_mask:0xf
	v_lshl_add_u32 v182, v182, 11, v103
	v_lshl_add_u32 v183, v183, 11, v103
	v_lshl_add_u32 v184, v184, 11, v103
	v_lshl_add_u32 v125, v125, 11, v103
	global_load_dwordx4 v[66:69], v182, s[16:17]
	global_load_dwordx4 v[74:77], v183, s[16:17]
	global_load_dwordx4 v[82:85], v184, s[16:17]
	global_load_dwordx4 v[90:93], v125, s[16:17]
	global_load_dwordx4 v[70:73], v182, s[16:17] offset:1024
	global_load_dwordx4 v[78:81], v183, s[16:17] offset:1024
	global_load_dwordx4 v[86:89], v184, s[16:17] offset:1024
	global_load_dwordx4 v[94:97], v125, s[16:17] offset:1024
	s_waitcnt vmcnt(16)
	ds_write_b64 v175, v[26:27] offset:8
	ds_write_b64 v175, v[28:29] offset:1032
	v_mov_b32_e32 v144, 0
	v_mov_b32_e32 v145, 0
	v_mov_b32_e32 v146, 0
	v_mov_b32_e32 v147, 0
	v_mov_b32_e32 v150, 0
	v_mov_b32_e32 v151, 0
	v_mov_b32_e32 v152, 0
	v_mov_b32_e32 v153, 0
	v_mov_b32_e32 v154, 0
	v_mov_b32_e32 v155, 0
	v_mov_b32_e32 v160, 0
	v_mov_b32_e32 v161, 0
	v_mov_b32_e32 v162, 0
	v_mov_b32_e32 v163, 0
	v_mov_b32_e32 v164, 0
	v_mov_b32_e32 v165, 0
	s_mov_b32 s10, 0
